# swiglu GEMM units: the first wave half takes its alignment barrier after the first eighth of its epilogue instead of before it (epilogue start overlaps the other half's last MFMA segment)
# baseline (speedup 1.0000x reference)
; #define PG8_BAR __builtin_amdgcn_s_barrier()
; template <class Epi>
; __device__ __forceinline__ void gemm_phase(LAS unsigned char* lds, const Gemm g, const TabSched& S, const Epi& E) {
;     ...
;         if (wr == 0) PG8_BAR;
;         E(acc, cur, wr, wc, fr, fq);
.Lk1_exit:
	s_cmp_eq_u32 s71, 2
	s_cbranch_scc1 .LBB0_420
	s_and_b64 vcc, exec, s[6:7]
	s_cbranch_vccz .LBB0_420

; __device__ __forceinline__ unsigned cvtpk(float lo, float hi) { f32x2 v = {lo, hi}; bf16x2_t b = __builtin_convertvector(v, bf16x2_t); return __builtin_bit_cast(unsigned, b); }
; __device__ __forceinline__ float sigmoidf_(float x) { return fast_rcp(1.f + __expf(-x)); }
; #define PG8_BAR __builtin_amdgcn_s_barrier()
;     __device__ __forceinline__ void operator()(const f32x4 (&acc)[2][2][4][2], const Unit& u, int wr, int wc, int fr, int fq) const {
;     ...
;         if (mode == 2) {
;             const int par = fq & 1;
; #pragma unroll
;             for (int ai = 0; ai < 2; ++ai)
; #pragma unroll
;                 for (int bj = 0; bj < 2; ++bj) { const int acol = ((u.pn * BM + bj * HALF + wc * 32) >> 1) + 4 * (fq - par);
; #pragma unroll
;                     for (int mp = 0; mp < 4; mp += 2) {
;                         u32x2 wk[2];
; #pragma unroll
;                         for (int q = 0; q < 2; ++q) { const f32x4 v0 = acc[ai][bj][mp + q][0], v1 = acc[ai][bj][mp + q][1]; float r[4];
; #pragma unroll
;                             for (int e = 0; e < 4; ++e) r[e] = v0[e] * sigmoidf_(v0[e]) * v1[e];
;                             wk[q].x = cvtpk(r[0], r[1]); wk[q].y = cvtpk(r[2], r[3]); }
;                         const auto sx = __builtin_amdgcn_permlane16_swap(wk[0].x, wk[1].x, false, false);
;                         const auto sy = __builtin_amdgcn_permlane16_swap(wk[0].y, wk[1].y, false, false);
;                         u32x4 w; w.x = sx[0]; w.y = sy[0]; w.z = sx[1]; w.w = sy[1];
;                         const size_t row = (size_t)(u.pm * BM + rl0 + ai * HALF + (mp + par) * 16);
;                         *(u32x4*)(O + row * ldc + acol) = w; } }
; template <class Epi>
; __device__ __forceinline__ void gemm_phase(LAS unsigned char* lds, const Gemm g, const TabSched& S, const Epi& E) {
;     ...
;         if (wr == 0) PG8_BAR;
.LBB0_737:
	v_mul_f32_e32 v138, 0xbfb8aa3b, v132
	v_mul_f32_e32 v139, 0xbfb8aa3b, v133
	v_exp_f32_e32 v138, v138
	v_exp_f32_e32 v139, v139
	s_lshl_b32 s13, s69, 8
	s_or_b32 s13, s13, s61
	v_add_f32_e32 v138, 1.0, v138
	v_add_f32_e32 v139, 1.0, v139
	v_rcp_f32_e32 v138, v138
	v_rcp_f32_e32 v139, v139
	s_ashr_i32 s13, s13, 1
	v_or_b32_e32 v136, s13, v180
	s_lshl_b32 s13, s68, 8
	v_pk_mul_f32 v[132:133], v[132:133], v[138:139]
	v_ashrrev_i32_e32 v137, 31, v136
	v_pk_mul_f32 v[128:129], v[128:129], v[132:133]
	v_mul_f32_e32 v132, 0xbfb8aa3b, v134
	v_mul_f32_e32 v133, 0xbfb8aa3b, v135
	v_exp_f32_e32 v132, v132
	v_exp_f32_e32 v133, v133
	v_cvt_pk_bf16_f32 v128, v128, v129
	v_add_f32_e32 v132, 1.0, v132
	v_add_f32_e32 v133, 1.0, v133
	v_rcp_f32_e32 v132, v132
	v_rcp_f32_e32 v133, v133
	s_nop 0
	v_pk_mul_f32 v[132:133], v[134:135], v[132:133]
	s_nop 0
	v_pk_mul_f32 v[130:131], v[130:131], v[132:133]
	s_nop 0
	v_cvt_pk_bf16_f32 v129, v130, v131
	v_mul_f32_e32 v130, 0xbfb8aa3b, v124
	v_mul_f32_e32 v131, 0xbfb8aa3b, v125
	v_exp_f32_e32 v130, v130
	v_exp_f32_e32 v131, v131
	v_add_f32_e32 v130, 1.0, v130
	v_add_f32_e32 v131, 1.0, v131
	v_rcp_f32_e32 v130, v130
	v_rcp_f32_e32 v131, v131
	s_nop 0
	v_pk_mul_f32 v[124:125], v[124:125], v[130:131]
	s_nop 0
	v_pk_mul_f32 v[120:121], v[120:121], v[124:125]
	v_mul_f32_e32 v124, 0xbfb8aa3b, v126
	v_mul_f32_e32 v125, 0xbfb8aa3b, v127
	v_exp_f32_e32 v124, v124
	v_exp_f32_e32 v125, v125
	v_cvt_pk_bf16_f32 v130, v120, v121
	s_nop 1
	v_permlane16_swap_b32_e32 v128, v130
	v_add_f32_e32 v124, 1.0, v124
	v_add_f32_e32 v125, 1.0, v125
	v_rcp_f32_e32 v124, v124
	v_rcp_f32_e32 v125, v125
	s_nop 0
	v_pk_mul_f32 v[124:125], v[126:127], v[124:125]
	s_nop 0
	v_pk_mul_f32 v[122:123], v[122:123], v[124:125]
	v_mul_f32_e32 v125, 0xbfb8aa3b, v116
	v_exp_f32_e32 v125, v125
	v_or_b32_e32 v124, s13, v181
	v_add_u32_e32 v120, v184, v124
	v_ashrrev_i32_e32 v121, 31, v120
	v_add_f32_e32 v125, 1.0, v125
	v_rcp_f32_e32 v126, v125
	v_mul_f32_e32 v125, 0xbfb8aa3b, v117
	v_exp_f32_e32 v125, v125
	v_cvt_pk_bf16_f32 v131, v122, v123
	v_mul_lo_u32 v122, s0, v121
	v_mul_lo_u32 v123, s1, v120
	v_add_f32_e32 v125, 1.0, v125
	v_rcp_f32_e32 v127, v125
	v_mad_u64_u32 v[120:121], s[26:27], s0, v120, 0
	v_add3_u32 v121, v121, v122, v123
	v_pk_mul_f32 v[116:117], v[116:117], v[126:127]
	v_lshl_add_u64 v[122:123], v[120:121], 1, s[24:25]
	v_pk_mul_f32 v[112:113], v[112:113], v[116:117]
	v_mul_f32_e32 v116, 0xbfb8aa3b, v118
	v_mul_f32_e32 v117, 0xbfb8aa3b, v119
	v_exp_f32_e32 v116, v116
	v_exp_f32_e32 v117, v117
	v_cvt_pk_bf16_f32 v112, v112, v113
	v_lshlrev_b64 v[120:121], 1, v[136:137]
	v_add_f32_e32 v116, 1.0, v116
	v_add_f32_e32 v117, 1.0, v117
	v_rcp_f32_e32 v116, v116
	v_rcp_f32_e32 v117, v117
	v_permlane16_swap_b32_e32 v129, v131
	v_lshl_add_u64 v[122:123], v[122:123], 0, v[120:121]
	v_pk_mul_f32 v[116:117], v[118:119], v[116:117]
	global_store_dwordx4 v[122:123], v[128:131], off
	s_and_b64 vcc, exec, s[6:7]
	s_cbranch_vccz .Lsw_nb
	s_barrier
.Lsw_nb:
	v_pk_mul_f32 v[114:115], v[114:115], v[116:117]
	s_nop 0
	v_cvt_pk_bf16_f32 v113, v114, v115
	v_mul_f32_e32 v114, 0xbfb8aa3b, v108
	v_mul_f32_e32 v115, 0xbfb8aa3b, v109
	v_exp_f32_e32 v114, v114
	v_exp_f32_e32 v115, v115
	v_add_f32_e32 v114, 1.0, v114
	v_add_f32_e32 v115, 1.0, v115
	v_rcp_f32_e32 v114, v114
	v_rcp_f32_e32 v115, v115
	s_nop 0
	v_pk_mul_f32 v[108:109], v[108:109], v[114:115]
	s_nop 0
	v_pk_mul_f32 v[104:105], v[104:105], v[108:109]
	v_mul_f32_e32 v108, 0xbfb8aa3b, v110
	v_mul_f32_e32 v109, 0xbfb8aa3b, v111
	v_exp_f32_e32 v108, v108
	v_exp_f32_e32 v109, v109
	v_cvt_pk_bf16_f32 v114, v104, v105
	s_nop 1
	v_permlane16_swap_b32_e32 v112, v114
	v_add_f32_e32 v108, 1.0, v108
	v_add_f32_e32 v109, 1.0, v109
	v_rcp_f32_e32 v108, v108
	v_rcp_f32_e32 v109, v109
	s_nop 0
	v_pk_mul_f32 v[108:109], v[110:111], v[108:109]
	s_nop 0
	v_pk_mul_f32 v[106:107], v[106:107], v[108:109]
	s_nop 0
	v_cvt_pk_bf16_f32 v115, v106, v107
	v_or_b32_e32 v106, s13, v182
	v_add_u32_e32 v104, v184, v106
	v_ashrrev_i32_e32 v105, 31, v104
	v_mul_lo_u32 v107, s0, v105
	v_mul_lo_u32 v108, s1, v104
	v_mad_u64_u32 v[104:105], s[26:27], s0, v104, 0
	v_add3_u32 v105, v105, v107, v108
	v_mul_f32_e32 v107, 0xbfb8aa3b, v100
	v_exp_f32_e32 v107, v107
	v_lshl_add_u64 v[104:105], v[104:105], 1, s[24:25]
	v_permlane16_swap_b32_e32 v113, v115
	v_add_f32_e32 v107, 1.0, v107
	v_rcp_f32_e32 v108, v107
	v_mul_f32_e32 v107, 0xbfb8aa3b, v101
	v_exp_f32_e32 v107, v107
	v_lshl_add_u64 v[104:105], v[104:105], 0, v[120:121]
	global_store_dwordx4 v[104:105], v[112:115], off
	v_add_f32_e32 v107, 1.0, v107
	v_rcp_f32_e32 v109, v107
	s_nop 0
	v_pk_mul_f32 v[100:101], v[100:101], v[108:109]
	s_nop 0
	v_pk_mul_f32 v[96:97], v[96:97], v[100:101]
	v_mul_f32_e32 v100, 0xbfb8aa3b, v102
	v_mul_f32_e32 v101, 0xbfb8aa3b, v103
	v_exp_f32_e32 v100, v100
	v_exp_f32_e32 v101, v101
	v_cvt_pk_bf16_f32 v96, v96, v97
	v_add_f32_e32 v100, 1.0, v100
	v_add_f32_e32 v101, 1.0, v101
	v_rcp_f32_e32 v100, v100
	v_rcp_f32_e32 v101, v101
	s_nop 0
	v_pk_mul_f32 v[100:101], v[102:103], v[100:101]
	s_nop 0
	v_pk_mul_f32 v[98:99], v[98:99], v[100:101]
	s_nop 0
	v_cvt_pk_bf16_f32 v97, v98, v99
	v_mul_f32_e32 v98, 0xbfb8aa3b, v92
	v_mul_f32_e32 v99, 0xbfb8aa3b, v93
	v_exp_f32_e32 v98, v98
	v_exp_f32_e32 v99, v99
	v_add_f32_e32 v98, 1.0, v98
	v_add_f32_e32 v99, 1.0, v99
	v_rcp_f32_e32 v98, v98
	v_rcp_f32_e32 v99, v99
	s_nop 0
	v_pk_mul_f32 v[92:93], v[92:93], v[98:99]
	s_nop 0
	v_pk_mul_f32 v[88:89], v[88:89], v[92:93]
	v_mul_f32_e32 v92, 0xbfb8aa3b, v94
	v_cvt_pk_bf16_f32 v98, v88, v89
	v_mul_f32_e32 v88, 0xbfb8aa3b, v84
	v_mul_f32_e32 v89, 0xbfb8aa3b, v85
	v_exp_f32_e32 v88, v88
; __device__ __forceinline__ unsigned cvtpk(float lo, float hi) { f32x2 v = {lo, hi}; bf16x2_t b = __builtin_convertvector(v, bf16x2_t); return __builtin_bit_cast(unsigned, b); }
; __device__ __forceinline__ float sigmoidf_(float x) { return fast_rcp(1.f + __expf(-x)); }
;     __device__ __forceinline__ void operator()(const f32x4 (&acc)[2][2][4][2], const Unit& u, int wr, int wc, int fr, int fq) const {
;     ...
;             for (int ai = 0; ai < 2; ++ai)
; #pragma unroll
;                 for (int bj = 0; bj < 2; ++bj) { const int acol = ((u.pn * BM + bj * HALF + wc * 32) >> 1) + 4 * (fq - par);
; #pragma unroll
;                     for (int mp = 0; mp < 4; mp += 2) {
;                         u32x2 wk[2];
; #pragma unroll
;                         for (int q = 0; q < 2; ++q) { const f32x4 v0 = acc[ai][bj][mp + q][0], v1 = acc[ai][bj][mp + q][1]; float r[4];
; #pragma unroll
;                             for (int e = 0; e < 4; ++e) r[e] = v0[e] * sigmoidf_(v0[e]) * v1[e];
;                             wk[q].x = cvtpk(r[0], r[1]); wk[q].y = cvtpk(r[2], r[3]); }
;                         const auto sx = __builtin_amdgcn_permlane16_swap(wk[0].x, wk[1].x, false, false);
;                         const auto sy = __builtin_amdgcn_permlane16_swap(wk[0].y, wk[1].y, false, false);
;                         u32x4 w; w.x = sx[0]; w.y = sy[0]; w.z = sx[1]; w.w = sy[1];
;                         const size_t row = (size_t)(u.pm * BM + rl0 + ai * HALF + (mp + par) * 16);
;                         *(u32x4*)(O + row * ldc + acol) = w; } }
	v_exp_f32_e32 v89, v89
	v_mul_f32_e32 v93, 0xbfb8aa3b, v95
	v_exp_f32_e32 v92, v92
	v_add_f32_e32 v88, 1.0, v88
	v_add_f32_e32 v89, 1.0, v89
	v_rcp_f32_e32 v88, v88
	v_rcp_f32_e32 v89, v89
	v_exp_f32_e32 v93, v93
	v_add_f32_e32 v92, 1.0, v92
	v_rcp_f32_e32 v92, v92
	v_pk_mul_f32 v[84:85], v[84:85], v[88:89]
	v_add_f32_e32 v93, 1.0, v93
	v_pk_mul_f32 v[80:81], v[80:81], v[84:85]
	v_mul_f32_e32 v84, 0xbfb8aa3b, v86
	v_mul_f32_e32 v85, 0xbfb8aa3b, v87
	v_exp_f32_e32 v84, v84
	v_exp_f32_e32 v85, v85
	v_cvt_pk_bf16_f32 v80, v80, v81
	v_rcp_f32_e32 v93, v93
	v_add_f32_e32 v84, 1.0, v84
	v_add_f32_e32 v85, 1.0, v85
	v_rcp_f32_e32 v84, v84
	v_rcp_f32_e32 v85, v85
	v_pk_mul_f32 v[92:93], v[94:95], v[92:93]
	v_permlane16_swap_b32_e32 v96, v98
	v_pk_mul_f32 v[84:85], v[86:87], v[84:85]
	v_pk_mul_f32 v[90:91], v[90:91], v[92:93]
	v_pk_mul_f32 v[82:83], v[82:83], v[84:85]
	v_cvt_pk_bf16_f32 v99, v90, v91
	v_cvt_pk_bf16_f32 v81, v82, v83
	v_mul_f32_e32 v82, 0xbfb8aa3b, v76
	v_mul_f32_e32 v83, 0xbfb8aa3b, v77
	v_exp_f32_e32 v82, v82
	v_exp_f32_e32 v83, v83
	v_permlane16_swap_b32_e32 v97, v99
	v_add_f32_e32 v82, 1.0, v82
	v_add_f32_e32 v83, 1.0, v83
	v_rcp_f32_e32 v82, v82
	v_rcp_f32_e32 v83, v83
	global_store_dwordx4 v[122:123], v[96:99], off offset:128
	v_pk_mul_f32 v[76:77], v[76:77], v[82:83]
	s_nop 0
	v_pk_mul_f32 v[72:73], v[72:73], v[76:77]
	v_mul_f32_e32 v76, 0xbfb8aa3b, v78
	v_cvt_pk_bf16_f32 v82, v72, v73
	v_mul_f32_e32 v72, 0xbfb8aa3b, v68
	v_mul_f32_e32 v73, 0xbfb8aa3b, v69
	v_exp_f32_e32 v72, v72
	v_exp_f32_e32 v73, v73
	v_mul_f32_e32 v77, 0xbfb8aa3b, v79
	v_exp_f32_e32 v76, v76
	v_add_f32_e32 v72, 1.0, v72
	v_add_f32_e32 v73, 1.0, v73
	v_rcp_f32_e32 v72, v72
	v_rcp_f32_e32 v73, v73
	v_exp_f32_e32 v77, v77
	v_add_f32_e32 v76, 1.0, v76
	v_rcp_f32_e32 v76, v76
	v_pk_mul_f32 v[68:69], v[68:69], v[72:73]
	v_add_f32_e32 v77, 1.0, v77
	v_pk_mul_f32 v[64:65], v[64:65], v[68:69]
	v_mul_f32_e32 v68, 0xbfb8aa3b, v70
	v_mul_f32_e32 v69, 0xbfb8aa3b, v71
	v_exp_f32_e32 v68, v68
	v_exp_f32_e32 v69, v69
	v_cvt_pk_bf16_f32 v64, v64, v65
	v_rcp_f32_e32 v77, v77
	v_add_f32_e32 v68, 1.0, v68
	v_add_f32_e32 v69, 1.0, v69
	v_rcp_f32_e32 v68, v68
	v_rcp_f32_e32 v69, v69
	v_pk_mul_f32 v[76:77], v[78:79], v[76:77]
	v_permlane16_swap_b32_e32 v80, v82
	v_pk_mul_f32 v[68:69], v[70:71], v[68:69]
	v_pk_mul_f32 v[74:75], v[74:75], v[76:77]
	v_pk_mul_f32 v[66:67], v[66:67], v[68:69]
	v_cvt_pk_bf16_f32 v83, v74, v75
	v_cvt_pk_bf16_f32 v65, v66, v67
	v_mul_f32_e32 v66, 0xbfb8aa3b, v60
	v_mul_f32_e32 v67, 0xbfb8aa3b, v61
	v_exp_f32_e32 v66, v66
	v_exp_f32_e32 v67, v67
	v_add_u32_e32 v74, 0x80, v184
	v_permlane16_swap_b32_e32 v81, v83
	v_add_f32_e32 v66, 1.0, v66
	v_add_f32_e32 v67, 1.0, v67
	v_rcp_f32_e32 v66, v66
	v_rcp_f32_e32 v67, v67
	global_store_dwordx4 v[104:105], v[80:83], off offset:128
	v_pk_mul_f32 v[60:61], v[60:61], v[66:67]
	s_nop 0
	v_pk_mul_f32 v[56:57], v[56:57], v[60:61]
	v_mul_f32_e32 v60, 0xbfb8aa3b, v62
	v_mul_f32_e32 v61, 0xbfb8aa3b, v63
	v_exp_f32_e32 v60, v60
	v_exp_f32_e32 v61, v61
	v_cvt_pk_bf16_f32 v66, v56, v57
	v_add_u32_e32 v56, v74, v124
	v_add_f32_e32 v60, 1.0, v60
	v_add_f32_e32 v61, 1.0, v61
	v_rcp_f32_e32 v60, v60
	v_rcp_f32_e32 v61, v61
	v_ashrrev_i32_e32 v57, 31, v56
	v_permlane16_swap_b32_e32 v64, v66
	v_pk_mul_f32 v[60:61], v[62:63], v[60:61]
	s_nop 0
	v_pk_mul_f32 v[58:59], v[58:59], v[60:61]
	s_nop 0
	v_cvt_pk_bf16_f32 v67, v58, v59
	v_mul_lo_u32 v58, s0, v57
	v_mul_lo_u32 v59, s1, v56
	v_mad_u64_u32 v[56:57], s[26:27], s0, v56, 0
	v_add3_u32 v57, v57, v58, v59
	v_mul_f32_e32 v58, 0xbfb8aa3b, v52
	v_mul_f32_e32 v59, 0xbfb8aa3b, v53
	v_exp_f32_e32 v58, v58
	v_exp_f32_e32 v59, v59
	v_lshl_add_u64 v[56:57], v[56:57], 1, s[24:25]
	v_permlane16_swap_b32_e32 v65, v67
	v_add_f32_e32 v58, 1.0, v58
	v_add_f32_e32 v59, 1.0, v59
	v_rcp_f32_e32 v58, v58
	v_rcp_f32_e32 v59, v59
	v_lshl_add_u64 v[56:57], v[56:57], 0, v[120:121]
	global_store_dwordx4 v[56:57], v[64:67], off
	v_pk_mul_f32 v[52:53], v[52:53], v[58:59]
	s_nop 0
	v_pk_mul_f32 v[48:49], v[48:49], v[52:53]
	v_mul_f32_e32 v52, 0xbfb8aa3b, v54
	v_mul_f32_e32 v53, 0xbfb8aa3b, v55
	v_exp_f32_e32 v52, v52
	v_exp_f32_e32 v53, v53
	v_cvt_pk_bf16_f32 v48, v48, v49
	v_add_f32_e32 v52, 1.0, v52
	v_add_f32_e32 v53, 1.0, v53
	v_rcp_f32_e32 v52, v52
	v_rcp_f32_e32 v53, v53
	s_nop 0
	v_pk_mul_f32 v[52:53], v[54:55], v[52:53]
	s_nop 0
	v_pk_mul_f32 v[50:51], v[50:51], v[52:53]
; __device__ __forceinline__ unsigned cvtpk(float lo, float hi) { f32x2 v = {lo, hi}; bf16x2_t b = __builtin_convertvector(v, bf16x2_t); return __builtin_bit_cast(unsigned, b); }
; __device__ __forceinline__ float sigmoidf_(float x) { return fast_rcp(1.f + __expf(-x)); }
;     __device__ __forceinline__ void operator()(const f32x4 (&acc)[2][2][4][2], const Unit& u, int wr, int wc, int fr, int fq) const {
;     ...
;             for (int ai = 0; ai < 2; ++ai)
; #pragma unroll
;                 for (int bj = 0; bj < 2; ++bj) { const int acol = ((u.pn * BM + bj * HALF + wc * 32) >> 1) + 4 * (fq - par);
; #pragma unroll
;                     for (int mp = 0; mp < 4; mp += 2) {
;                         u32x2 wk[2];
; #pragma unroll
;                         for (int q = 0; q < 2; ++q) { const f32x4 v0 = acc[ai][bj][mp + q][0], v1 = acc[ai][bj][mp + q][1]; float r[4];
; #pragma unroll
;                             for (int e = 0; e < 4; ++e) r[e] = v0[e] * sigmoidf_(v0[e]) * v1[e];
;                             wk[q].x = cvtpk(r[0], r[1]); wk[q].y = cvtpk(r[2], r[3]); }
;                         const auto sx = __builtin_amdgcn_permlane16_swap(wk[0].x, wk[1].x, false, false);
;                         const auto sy = __builtin_amdgcn_permlane16_swap(wk[0].y, wk[1].y, false, false);
;                         u32x4 w; w.x = sx[0]; w.y = sy[0]; w.z = sx[1]; w.w = sy[1];
;                         const size_t row = (size_t)(u.pm * BM + rl0 + ai * HALF + (mp + par) * 16);
;                         *(u32x4*)(O + row * ldc + acol) = w; } }
;             return;
; template <class Epi>
; __device__ __forceinline__ void gemm_phase(LAS unsigned char* lds, const Gemm g, const TabSched& S, const Epi& E) {
;     ...
;         if (!has_next) break;
	s_nop 0
	v_cvt_pk_bf16_f32 v49, v50, v51
	v_mul_f32_e32 v50, 0xbfb8aa3b, v44
	v_mul_f32_e32 v51, 0xbfb8aa3b, v45
	v_exp_f32_e32 v50, v50
	v_exp_f32_e32 v51, v51
	v_add_f32_e32 v50, 1.0, v50
	v_add_f32_e32 v51, 1.0, v51
	v_rcp_f32_e32 v50, v50
	v_rcp_f32_e32 v51, v51
	s_nop 0
	v_pk_mul_f32 v[44:45], v[44:45], v[50:51]
	s_nop 0
	v_pk_mul_f32 v[40:41], v[40:41], v[44:45]
	v_mul_f32_e32 v44, 0xbfb8aa3b, v46
	v_mul_f32_e32 v45, 0xbfb8aa3b, v47
	v_exp_f32_e32 v44, v44
	v_exp_f32_e32 v45, v45
	v_cvt_pk_bf16_f32 v50, v40, v41
	v_add_u32_e32 v40, v74, v106
	v_add_f32_e32 v44, 1.0, v44
	v_add_f32_e32 v45, 1.0, v45
	v_rcp_f32_e32 v44, v44
	v_rcp_f32_e32 v45, v45
	v_ashrrev_i32_e32 v41, 31, v40
	v_permlane16_swap_b32_e32 v48, v50
	v_pk_mul_f32 v[44:45], v[46:47], v[44:45]
	s_nop 0
	v_pk_mul_f32 v[42:43], v[42:43], v[44:45]
	s_nop 0
	v_cvt_pk_bf16_f32 v51, v42, v43
	v_mul_lo_u32 v42, s0, v41
	v_mul_lo_u32 v43, s1, v40
	v_mad_u64_u32 v[40:41], s[26:27], s0, v40, 0
	v_add3_u32 v41, v41, v42, v43
	v_mul_f32_e32 v42, 0xbfb8aa3b, v36
	v_mul_f32_e32 v43, 0xbfb8aa3b, v37
	v_exp_f32_e32 v42, v42
	v_exp_f32_e32 v43, v43
	v_lshl_add_u64 v[40:41], v[40:41], 1, s[24:25]
	v_permlane16_swap_b32_e32 v49, v51
	v_add_f32_e32 v42, 1.0, v42
	v_add_f32_e32 v43, 1.0, v43
	v_rcp_f32_e32 v42, v42
	v_rcp_f32_e32 v43, v43
	v_lshl_add_u64 v[40:41], v[40:41], 0, v[120:121]
	global_store_dwordx4 v[40:41], v[48:51], off
	v_pk_mul_f32 v[36:37], v[36:37], v[42:43]
	s_nop 0
	v_pk_mul_f32 v[32:33], v[32:33], v[36:37]
	v_mul_f32_e32 v36, 0xbfb8aa3b, v38
	v_mul_f32_e32 v37, 0xbfb8aa3b, v39
	v_exp_f32_e32 v36, v36
	v_exp_f32_e32 v37, v37
	v_cvt_pk_bf16_f32 v32, v32, v33
	v_add_f32_e32 v36, 1.0, v36
	v_add_f32_e32 v37, 1.0, v37
	v_rcp_f32_e32 v36, v36
	v_rcp_f32_e32 v37, v37
	s_nop 0
	v_pk_mul_f32 v[36:37], v[38:39], v[36:37]
	s_nop 0
	v_pk_mul_f32 v[34:35], v[34:35], v[36:37]
	s_nop 0
	v_cvt_pk_bf16_f32 v33, v34, v35
	v_mul_f32_e32 v34, 0xbfb8aa3b, v28
	v_mul_f32_e32 v35, 0xbfb8aa3b, v29
	v_exp_f32_e32 v34, v34
	v_exp_f32_e32 v35, v35
	v_add_f32_e32 v34, 1.0, v34
	v_add_f32_e32 v35, 1.0, v35
	v_rcp_f32_e32 v34, v34
	v_rcp_f32_e32 v35, v35
	s_nop 0
	v_pk_mul_f32 v[28:29], v[28:29], v[34:35]
	s_nop 0
	v_pk_mul_f32 v[24:25], v[24:25], v[28:29]
	v_mul_f32_e32 v28, 0xbfb8aa3b, v30
	v_cvt_pk_bf16_f32 v34, v24, v25
	v_mul_f32_e32 v24, 0xbfb8aa3b, v20
	v_mul_f32_e32 v25, 0xbfb8aa3b, v21
	v_exp_f32_e32 v24, v24
	v_exp_f32_e32 v25, v25
	v_mul_f32_e32 v29, 0xbfb8aa3b, v31
	v_exp_f32_e32 v28, v28
	v_add_f32_e32 v24, 1.0, v24
	v_add_f32_e32 v25, 1.0, v25
	v_rcp_f32_e32 v24, v24
	v_rcp_f32_e32 v25, v25
	v_exp_f32_e32 v29, v29
	v_add_f32_e32 v28, 1.0, v28
	v_rcp_f32_e32 v28, v28
	v_pk_mul_f32 v[20:21], v[20:21], v[24:25]
	v_add_f32_e32 v29, 1.0, v29
	v_pk_mul_f32 v[16:17], v[16:17], v[20:21]
	v_mul_f32_e32 v20, 0xbfb8aa3b, v22
	v_mul_f32_e32 v21, 0xbfb8aa3b, v23
	v_exp_f32_e32 v20, v20
	v_exp_f32_e32 v21, v21
	v_cvt_pk_bf16_f32 v16, v16, v17
	v_rcp_f32_e32 v29, v29
	v_add_f32_e32 v20, 1.0, v20
	v_add_f32_e32 v21, 1.0, v21
	v_rcp_f32_e32 v20, v20
	v_rcp_f32_e32 v21, v21
	v_pk_mul_f32 v[28:29], v[30:31], v[28:29]
	v_permlane16_swap_b32_e32 v32, v34
	v_pk_mul_f32 v[20:21], v[22:23], v[20:21]
	v_pk_mul_f32 v[26:27], v[26:27], v[28:29]
	v_pk_mul_f32 v[18:19], v[18:19], v[20:21]
	v_cvt_pk_bf16_f32 v35, v26, v27
	v_cvt_pk_bf16_f32 v17, v18, v19
	v_mul_f32_e32 v18, 0xbfb8aa3b, v12
	v_mul_f32_e32 v19, 0xbfb8aa3b, v13
	v_exp_f32_e32 v18, v18
	v_exp_f32_e32 v19, v19
	v_permlane16_swap_b32_e32 v33, v35
	v_add_f32_e32 v18, 1.0, v18
	v_add_f32_e32 v19, 1.0, v19
	v_rcp_f32_e32 v18, v18
	v_rcp_f32_e32 v19, v19
	global_store_dwordx4 v[56:57], v[32:35], off offset:128
	v_pk_mul_f32 v[12:13], v[12:13], v[18:19]
	s_nop 0
	v_pk_mul_f32 v[8:9], v[8:9], v[12:13]
	v_mul_f32_e32 v12, 0xbfb8aa3b, v14
	v_mul_f32_e32 v13, 0xbfb8aa3b, v15
	v_exp_f32_e32 v12, v12
	v_exp_f32_e32 v13, v13
	v_cvt_pk_bf16_f32 v18, v8, v9
	s_nop 1
	v_permlane16_swap_b32_e32 v16, v18
	v_add_f32_e32 v12, 1.0, v12
	v_add_f32_e32 v13, 1.0, v13
	v_rcp_f32_e32 v12, v12
	v_rcp_f32_e32 v13, v13
	s_nop 0
	v_pk_mul_f32 v[12:13], v[14:15], v[12:13]
	s_nop 0
	v_pk_mul_f32 v[10:11], v[10:11], v[12:13]
	s_nop 0
	v_cvt_pk_bf16_f32 v19, v10, v11
	s_nop 1
	v_permlane16_swap_b32_e32 v17, v19
	global_store_dwordx4 v[40:41], v[16:19], off offset:128
	s_andn2_b64 vcc, exec, s[44:45]
	s_mov_b64 s[26:27], -1
	s_cbranch_vccnz .LBB0_411
